# in-proj rope epilogue: touch loads for the second cache line of the cos/sin rows and for the next 32-row block when a block's first table loads issue
# baseline (speedup 1.0000x reference)
; template <int EPI>
; DI void phase_gemm(const Params& p, const GemmArgs& ga, char* lds) {
;     ...
; #pragma unroll
;         for (int mi = 0; mi < 4; ++mi) {
;           const int pos = pos0 + wm * 128 + mi * 32 + r;
;           float rs = 1.f;
;           if (nrm) {
;             float ss = 0.f;
; #pragma unroll
;             for (int i = 0; i < 16; ++i) ss += acc[mi][0][i] * acc[mi][0][i] + acc[mi][1][i] * acc[mi][1][i];
;             ss += __shfl_xor(ss, 32);
;             rs = rsqrtf(ss * (1.f / 64.f) + 1e-6f);
;           }
;           u16* q = QK + (size_t)(tokbase + pos) * QK0_LD + dcol + 8 * h;
;           const float* csr = cs + (size_t)pos * 64 + 8 * h;
; #pragma unroll
;           for (int jp = 0; jp < 2; ++jp) {
;             u32x2 v1[2], v2[2];
; #pragma unroll
;             for (int jj = 0; jj < 2; ++jj) {
;               const int j = 2 * jp + jj;
;               const float4 ca = *(const float4*)(csr + 16 * j);
;               const float4 cb = *(const float4*)(csr + 16 * j + 4);
.LBB0_338:
	s_or_b64 exec, exec, s[16:17]
	v_add_u32_e32 v152, s14, v189
	v_cndmask_b32_e32 v0, v223, v224, vcc
	v_mov_b32_e32 v161, v1
	v_ashrrev_i32_e32 v153, 31, v152
	v_lshl_add_u64 v[150:151], v[158:159], 0, v[0:1]
	v_lshl_add_u64 v[148:149], v[130:131], 0, v[160:161]
	v_lshlrev_b64 v[130:131], 8, v[152:153]
	v_lshl_add_u64 v[168:169], v[150:151], 0, v[130:131]
	global_load_dwordx4 v[130:133], v[168:169], off offset:16
	global_load_dwordx4 v[134:137], v[168:169], off
	global_load_dword v240, v[168:169], off offset:128
	s_movk_i32 s100, 0x2000
	v_add_co_u32_e64 v238, s[8:9], s100, v168
	v_addc_co_u32_e64 v239, s[8:9], 0, v169, s[8:9]
	global_load_dword v241, v[238:239], off
	global_load_dword v242, v[238:239], off offset:128
	v_mov_b32_e32 v176, v114
	s_and_saveexec_b64 s[8:9], vcc
	s_cbranch_execz .LBB0_340
	global_load_dwordx4 v[138:141], v[148:149], off
	s_waitcnt vmcnt(0)
	v_mov_b32_e32 v142, v139
	v_mov_b32_e32 v143, v140
	v_mul_f32_e32 v0, v166, v138
	v_pk_mul_f32 v[138:139], v[166:167], v[142:143] op_sel_hi:[0,1]
	v_mul_f32_e32 v176, v114, v0
	v_pk_mul_f32 v[172:173], v[172:173], v[138:139]
	v_mul_f32_e32 v0, v166, v141
	global_load_dwordx4 v[138:141], v[148:149], off offset:128
	v_mul_f32_e32 v147, v147, v0
	s_waitcnt vmcnt(0)
	v_pk_mul_f32 v[138:139], v[166:167], v[138:139] op_sel_hi:[0,1]
	v_pk_mul_f32 v[174:175], v[174:175], v[138:139]
	v_pk_mul_f32 v[138:139], v[166:167], v[140:141] op_sel_hi:[0,1]
	v_pk_mul_f32 v[170:171], v[170:171], v[138:139]

; template <int EPI>
; DI void phase_gemm(const Params& p, const GemmArgs& ga, char* lds) {
;     ...
; #pragma unroll
;         for (int mi = 0; mi < 4; ++mi) {
;           const int pos = pos0 + wm * 128 + mi * 32 + r;
;           float rs = 1.f;
;           if (nrm) {
;             float ss = 0.f;
; #pragma unroll
;             for (int i = 0; i < 16; ++i) ss += acc[mi][0][i] * acc[mi][0][i] + acc[mi][1][i] * acc[mi][1][i];
;             ss += __shfl_xor(ss, 32);
;             rs = rsqrtf(ss * (1.f / 64.f) + 1e-6f);
;           }
;           u16* q = QK + (size_t)(tokbase + pos) * QK0_LD + dcol + 8 * h;
;           const float* csr = cs + (size_t)pos * 64 + 8 * h;
; #pragma unroll
;           for (int jp = 0; jp < 2; ++jp) {
;             u32x2 v1[2], v2[2];
; #pragma unroll
;             for (int jj = 0; jj < 2; ++jj) {
;               const int j = 2 * jp + jj;
;               const float4 ca = *(const float4*)(csr + 16 * j);
;               const float4 cb = *(const float4*)(csr + 16 * j + 4);
.LBB0_350:
	s_or_b64 exec, exec, s[12:13]
	v_or_b32_e32 v174, 32, v152
	v_ashrrev_i32_e32 v175, 31, v174
	v_lshlrev_b64 v[130:131], 8, v[174:175]
	v_lshl_add_u64 v[166:167], v[150:151], 0, v[130:131]
	global_load_dwordx4 v[130:133], v[166:167], off offset:16
	global_load_dwordx4 v[134:137], v[166:167], off
	global_load_dword v240, v[166:167], off offset:128
	s_movk_i32 s100, 0x2000
	v_add_co_u32_e64 v238, s[8:9], s100, v166
	v_addc_co_u32_e64 v239, s[8:9], 0, v167, s[8:9]
	global_load_dword v241, v[238:239], off
	global_load_dword v242, v[238:239], off offset:128
	v_mov_b32_e32 v176, v98
	s_and_saveexec_b64 s[8:9], vcc
	s_cbranch_execz .LBB0_352
	global_load_dwordx4 v[138:141], v[148:149], off
	s_waitcnt vmcnt(0)
	v_mov_b32_e32 v142, v139
	v_mov_b32_e32 v143, v140
	v_mul_f32_e32 v138, v0, v138
	v_mul_f32_e32 v176, v98, v138
	v_pk_mul_f32 v[138:139], v[0:1], v[142:143] op_sel_hi:[0,1]
	v_pk_mul_f32 v[170:171], v[170:171], v[138:139]
	v_mul_f32_e32 v138, v0, v141
	v_mul_f32_e32 v153, v153, v138
	global_load_dwordx4 v[138:141], v[148:149], off offset:128
	s_waitcnt vmcnt(0)
	v_pk_mul_f32 v[138:139], v[0:1], v[138:139] op_sel_hi:[0,1]
	v_pk_mul_f32 v[172:173], v[172:173], v[138:139]
	v_pk_mul_f32 v[138:139], v[0:1], v[140:141] op_sel_hi:[0,1]
	v_pk_mul_f32 v[168:169], v[168:169], v[138:139]

; template <int EPI>
; DI void phase_gemm(const Params& p, const GemmArgs& ga, char* lds) {
;     ...
; #pragma unroll
;         for (int mi = 0; mi < 4; ++mi) {
;           const int pos = pos0 + wm * 128 + mi * 32 + r;
;           float rs = 1.f;
;           if (nrm) {
;             float ss = 0.f;
; #pragma unroll
;             for (int i = 0; i < 16; ++i) ss += acc[mi][0][i] * acc[mi][0][i] + acc[mi][1][i] * acc[mi][1][i];
;             ss += __shfl_xor(ss, 32);
;             rs = rsqrtf(ss * (1.f / 64.f) + 1e-6f);
;           }
;           u16* q = QK + (size_t)(tokbase + pos) * QK0_LD + dcol + 8 * h;
;           const float* csr = cs + (size_t)pos * 64 + 8 * h;
; #pragma unroll
;           for (int jp = 0; jp < 2; ++jp) {
;             u32x2 v1[2], v2[2];
; #pragma unroll
;             for (int jj = 0; jj < 2; ++jj) {
;               const int j = 2 * jp + jj;
;               const float4 ca = *(const float4*)(csr + 16 * j);
;               const float4 cb = *(const float4*)(csr + 16 * j + 4);
.LBB0_362:
	s_or_b64 exec, exec, s[12:13]
	v_or_b32_e32 v174, 64, v152
	v_ashrrev_i32_e32 v175, 31, v174
	v_lshlrev_b64 v[130:131], 8, v[174:175]
	v_lshl_add_u64 v[166:167], v[150:151], 0, v[130:131]
	global_load_dwordx4 v[130:133], v[166:167], off offset:16
	global_load_dwordx4 v[134:137], v[166:167], off
	global_load_dword v240, v[166:167], off offset:128
	s_movk_i32 s100, 0x2000
	v_add_co_u32_e64 v238, s[8:9], s100, v166
	v_addc_co_u32_e64 v239, s[8:9], 0, v167, s[8:9]
	global_load_dword v241, v[238:239], off
	global_load_dword v242, v[238:239], off offset:128
	v_mov_b32_e32 v176, v66
	s_and_saveexec_b64 s[8:9], vcc
	s_cbranch_execz .LBB0_364
	global_load_dwordx4 v[138:141], v[148:149], off
	s_waitcnt vmcnt(0)
	v_mov_b32_e32 v142, v139
	v_mov_b32_e32 v143, v140
	v_mul_f32_e32 v138, v0, v138
	v_mul_f32_e32 v176, v66, v138
	v_pk_mul_f32 v[138:139], v[0:1], v[142:143] op_sel_hi:[0,1]
	v_pk_mul_f32 v[170:171], v[170:171], v[138:139]
	v_mul_f32_e32 v138, v0, v141
	v_mul_f32_e32 v153, v153, v138
	global_load_dwordx4 v[138:141], v[148:149], off offset:128
	s_waitcnt vmcnt(0)
	v_pk_mul_f32 v[138:139], v[0:1], v[138:139] op_sel_hi:[0,1]
	v_pk_mul_f32 v[172:173], v[172:173], v[138:139]
	v_pk_mul_f32 v[138:139], v[0:1], v[140:141] op_sel_hi:[0,1]
	v_pk_mul_f32 v[168:169], v[168:169], v[138:139]

; template <int EPI>
; DI void phase_gemm(const Params& p, const GemmArgs& ga, char* lds) {
;     ...
; #pragma unroll
;         for (int mi = 0; mi < 4; ++mi) {
;           const int pos = pos0 + wm * 128 + mi * 32 + r;
;           float rs = 1.f;
;           if (nrm) {
;             float ss = 0.f;
; #pragma unroll
;             for (int i = 0; i < 16; ++i) ss += acc[mi][0][i] * acc[mi][0][i] + acc[mi][1][i] * acc[mi][1][i];
;             ss += __shfl_xor(ss, 32);
;             rs = rsqrtf(ss * (1.f / 64.f) + 1e-6f);
;           }
;           u16* q = QK + (size_t)(tokbase + pos) * QK0_LD + dcol + 8 * h;
;           const float* csr = cs + (size_t)pos * 64 + 8 * h;
; #pragma unroll
;           for (int jp = 0; jp < 2; ++jp) {
;             u32x2 v1[2], v2[2];
; #pragma unroll
;             for (int jj = 0; jj < 2; ++jj) {
;               const int j = 2 * jp + jj;
;               const float4 ca = *(const float4*)(csr + 16 * j);
;               const float4 cb = *(const float4*)(csr + 16 * j + 4);
.LBB0_374:
	s_or_b64 exec, exec, s[8:9]
	v_or_b32_e32 v152, 0x60, v152
	v_ashrrev_i32_e32 v153, 31, v152
	v_lshlrev_b64 v[130:131], 8, v[152:153]
	v_lshl_add_u64 v[150:151], v[150:151], 0, v[130:131]
	global_load_dwordx4 v[130:133], v[150:151], off offset:16
	global_load_dwordx4 v[134:137], v[150:151], off
	global_load_dword v240, v[150:151], off offset:128
	v_mov_b32_e32 v172, v34
	s_and_saveexec_b64 s[6:7], vcc
	s_cbranch_execz .LBB0_376
	global_load_dwordx4 v[138:141], v[148:149], off
	s_waitcnt vmcnt(0)
	v_mov_b32_e32 v142, v139
	v_mov_b32_e32 v143, v140
	v_mul_f32_e32 v138, v0, v138
	v_mul_f32_e32 v172, v34, v138
	v_pk_mul_f32 v[138:139], v[0:1], v[142:143] op_sel_hi:[0,1]
	v_pk_mul_f32 v[168:169], v[168:169], v[138:139]
	v_mul_f32_e32 v138, v0, v141
	v_mul_f32_e32 v161, v161, v138
	global_load_dwordx4 v[138:141], v[148:149], off offset:128
	s_waitcnt vmcnt(0)
	v_pk_mul_f32 v[138:139], v[0:1], v[138:139] op_sel_hi:[0,1]
	v_pk_mul_f32 v[170:171], v[170:171], v[138:139]
	v_pk_mul_f32 v[138:139], v[0:1], v[140:141] op_sel_hi:[0,1]
	v_pk_mul_f32 v[166:167], v[166:167], v[138:139]
